# step13: + proj1 K-tile fp32 staging uses gains preloaded once per tile (3 of 4 vectors) instead of 32 serialized loads
# speedup vs baseline: 1.0169x; 1.0011x over previous
.LBB0_816:
	ds_read_b128 v[138:141], v136
	ds_read_b128 v[142:145], v135
	ds_read_b128 v[218:221], v135 offset:16896
	ds_read_b128 v[222:225], v137
	v_add_u32_e32 v226, s6, v134
	v_add_u32_e32 v228, s6, v133
	v_add_u32_e32 v230, s6, v132
	v_ashrrev_i32_e32 v227, 31, v226
	v_add_u32_e32 v232, 32, v226
	s_add_i32 s6, s6, 64
	v_ashrrev_i32_e32 v229, 31, v228
	v_ashrrev_i32_e32 v231, 31, v230
	v_lshlrev_b64 v[226:227], 12, v[226:227]
	v_ashrrev_i32_e32 v233, 31, v232
	v_add_u32_e32 v137, 0x8400, v137
	v_add_u32_e32 v136, 0x8400, v136
	v_add_u32_e32 v135, 0x8400, v135
	s_cmpk_eq_i32 s6, 0x100
	v_lshlrev_b64 v[228:229], 12, v[228:229]
	v_lshlrev_b64 v[230:231], 12, v[230:231]
	v_lshl_add_u64 v[226:227], v[130:131], 0, v[226:227]
	v_lshlrev_b64 v[232:233], 12, v[232:233]
	v_lshl_add_u64 v[228:229], v[130:131], 0, v[228:229]
	v_lshl_add_u64 v[230:231], v[130:131], 0, v[230:231]
	v_lshl_add_u64 v[232:233], v[130:131], 0, v[232:233]
	s_waitcnt lgkmcnt(2)
	global_store_dwordx4 v[226:227], v[142:145], off
	global_store_dwordx4 v[228:229], v[138:141], off
	s_waitcnt lgkmcnt(1)
	global_store_dwordx4 v[232:233], v[218:221], off
	s_waitcnt lgkmcnt(0)
	global_store_dwordx4 v[230:231], v[222:225], off
	s_cbranch_scc0 .LBB0_816
	s_and_b64 vcc, exec, s[34:35]
	s_barrier
	s_cbranch_vccz .LBB0_955
	v_cndmask_b32_e64 v130, 0, 1, s[38:39]
	v_cmp_ne_u32_e64 s[6:7], 1, v130
	s_nop 1
	s_and_b64 vcc, exec, s[6:7]
	s_cbranch_vccnz .Lp1_nogain
	global_load_dwordx4 v[240:243], v[150:151], off
	global_load_dwordx4 v[244:247], v[150:151], off offset:64
	global_load_dwordx4 v[248:251], v[150:151], off offset:128
	s_waitcnt vmcnt(0)
.Lp1_nogain:
	s_and_saveexec_b64 s[42:43], s[8:9]
	s_cbranch_execz .LBB0_884
	v_mov_b32_e32 v133, 1.0
	s_and_b64 vcc, exec, s[6:7]
	v_mov_b32_e32 v137, 1.0
	v_mov_b32_e32 v136, 1.0
	v_mov_b32_e32 v135, 1.0
	v_mov_b32_e32 v134, 1.0
	s_cbranch_vccnz .LBB0_821
	v_mov_b32_e32 v134, v240
	v_mov_b32_e32 v135, v241
	v_mov_b32_e32 v136, v242
	v_mov_b32_e32 v137, v243
.LBB0_821:
	v_mul_f32_e32 v130, v126, v217
	v_mul_f32_e32 v134, v130, v134
	v_mul_f32_e32 v130, v127, v217
	v_mul_f32_e32 v135, v130, v135
	v_mul_f32_e32 v130, v128, v217
	v_mul_f32_e32 v136, v130, v136
	v_mul_f32_e32 v130, v129, v217
	v_mul_f32_e32 v137, v130, v137
	s_and_b64 vcc, exec, s[6:7]
	v_mov_b32_e32 v132, 1.0
	v_mov_b32_e32 v131, 1.0
	v_mov_b32_e32 v130, 1.0
	ds_write_b128 v193, v[134:137]
	s_cbranch_vccnz .LBB0_823
	v_mov_b32_e32 v130, v244
	v_mov_b32_e32 v131, v245
	v_mov_b32_e32 v132, v246
	v_mov_b32_e32 v133, v247
.LBB0_823:
	v_mul_f32_e32 v134, v122, v217
	v_mul_f32_e32 v130, v134, v130
	v_mul_f32_e32 v134, v123, v217
	v_mul_f32_e32 v131, v134, v131
	v_mul_f32_e32 v134, v124, v217
	v_mul_f32_e32 v132, v134, v132
	v_mul_f32_e32 v134, v125, v217
	v_mul_f32_e32 v133, v134, v133
	ds_write_b128 v193, v[130:133] offset:64
	v_mov_b32_e32 v133, 1.0
	s_and_b64 vcc, exec, s[6:7]
	v_mov_b32_e32 v137, 1.0
	v_mov_b32_e32 v136, 1.0
	v_mov_b32_e32 v135, 1.0
	v_mov_b32_e32 v134, 1.0
	s_cbranch_vccnz .LBB0_825
	v_mov_b32_e32 v134, v248
	v_mov_b32_e32 v135, v249
	v_mov_b32_e32 v136, v250
	v_mov_b32_e32 v137, v251

.LBB0_827:
	v_mul_f32_e32 v134, v114, v217
	v_mul_f32_e32 v130, v134, v130
	v_mul_f32_e32 v134, v115, v217
	v_mul_f32_e32 v131, v134, v131
	v_mul_f32_e32 v134, v116, v217
	v_mul_f32_e32 v132, v134, v132
	v_mul_f32_e32 v134, v117, v217
	v_mul_f32_e32 v133, v134, v133
	ds_write_b128 v193, v[130:133] offset:192
	v_mov_b32_e32 v133, 1.0
	s_and_b64 vcc, exec, s[6:7]
	v_mov_b32_e32 v137, 1.0
	v_mov_b32_e32 v136, 1.0
	v_mov_b32_e32 v135, 1.0
	v_mov_b32_e32 v134, 1.0
	s_cbranch_vccnz .LBB0_829
	v_mov_b32_e32 v134, v240
	v_mov_b32_e32 v135, v241
	v_mov_b32_e32 v136, v242
	v_mov_b32_e32 v137, v243
.LBB0_829:
	v_mul_f32_e32 v130, v110, v216
	v_mul_f32_e32 v134, v130, v134
	v_mul_f32_e32 v130, v111, v216
	v_mul_f32_e32 v135, v130, v135
	v_mul_f32_e32 v130, v112, v216
	v_mul_f32_e32 v136, v130, v136
	v_mul_f32_e32 v130, v113, v216
	v_mul_f32_e32 v137, v130, v137
	s_and_b64 vcc, exec, s[6:7]
	v_mov_b32_e32 v132, 1.0
	v_mov_b32_e32 v131, 1.0
	v_mov_b32_e32 v130, 1.0
	ds_write_b128 v193, v[134:137] offset:16640
	s_cbranch_vccnz .LBB0_831
	v_mov_b32_e32 v130, v244
	v_mov_b32_e32 v131, v245
	v_mov_b32_e32 v132, v246
	v_mov_b32_e32 v133, v247
.LBB0_831:
	v_mul_f32_e32 v134, v106, v216
	v_mul_f32_e32 v130, v134, v130
	v_mul_f32_e32 v134, v107, v216
	v_mul_f32_e32 v131, v134, v131
	v_mul_f32_e32 v134, v108, v216
	v_mul_f32_e32 v132, v134, v132
	v_mul_f32_e32 v134, v109, v216
	v_mul_f32_e32 v133, v134, v133
	ds_write_b128 v193, v[130:133] offset:16704
	v_mov_b32_e32 v133, 1.0
	s_and_b64 vcc, exec, s[6:7]
	v_mov_b32_e32 v137, 1.0
	v_mov_b32_e32 v136, 1.0
	v_mov_b32_e32 v135, 1.0
	v_mov_b32_e32 v134, 1.0
	s_cbranch_vccnz .LBB0_833
	v_mov_b32_e32 v134, v248
	v_mov_b32_e32 v135, v249
	v_mov_b32_e32 v136, v250
	v_mov_b32_e32 v137, v251

.LBB0_835:
	v_mul_f32_e32 v134, v98, v216
	v_mul_f32_e32 v130, v134, v130
	v_mul_f32_e32 v134, v99, v216
	v_mul_f32_e32 v131, v134, v131
	v_mul_f32_e32 v134, v100, v216
	v_mul_f32_e32 v132, v134, v132
	v_mul_f32_e32 v134, v101, v216
	v_mul_f32_e32 v133, v134, v133
	ds_write_b128 v193, v[130:133] offset:16832
	v_mov_b32_e32 v133, 1.0
	s_and_b64 vcc, exec, s[6:7]
	v_mov_b32_e32 v137, 1.0
	v_mov_b32_e32 v136, 1.0
	v_mov_b32_e32 v135, 1.0
	v_mov_b32_e32 v134, 1.0
	s_cbranch_vccnz .LBB0_837
	v_mov_b32_e32 v134, v240
	v_mov_b32_e32 v135, v241
	v_mov_b32_e32 v136, v242
	v_mov_b32_e32 v137, v243
.LBB0_837:
	v_mul_f32_e32 v130, v94, v215
	v_mul_f32_e32 v134, v130, v134
	v_mul_f32_e32 v130, v95, v215
	v_mul_f32_e32 v135, v130, v135
	v_mul_f32_e32 v130, v96, v215
	v_mul_f32_e32 v136, v130, v136
	v_mul_f32_e32 v130, v97, v215
	v_mul_f32_e32 v137, v130, v137
	s_and_b64 vcc, exec, s[6:7]
	v_mov_b32_e32 v132, 1.0
	v_mov_b32_e32 v131, 1.0
	v_mov_b32_e32 v130, 1.0
	ds_write_b128 v193, v[134:137] offset:33280
	s_cbranch_vccnz .LBB0_839
	v_mov_b32_e32 v130, v244
	v_mov_b32_e32 v131, v245
	v_mov_b32_e32 v132, v246
	v_mov_b32_e32 v133, v247
.LBB0_839:
	v_mul_f32_e32 v134, v90, v215
	v_mul_f32_e32 v130, v134, v130
	v_mul_f32_e32 v134, v91, v215
	v_mul_f32_e32 v131, v134, v131
	v_mul_f32_e32 v134, v92, v215
	v_mul_f32_e32 v132, v134, v132
	v_mul_f32_e32 v134, v93, v215
	v_mul_f32_e32 v133, v134, v133
	ds_write_b128 v193, v[130:133] offset:33344
	v_mov_b32_e32 v133, 1.0
	s_and_b64 vcc, exec, s[6:7]
	v_mov_b32_e32 v137, 1.0
	v_mov_b32_e32 v136, 1.0
	v_mov_b32_e32 v135, 1.0
	v_mov_b32_e32 v134, 1.0
	s_cbranch_vccnz .LBB0_841
	v_mov_b32_e32 v134, v248
	v_mov_b32_e32 v135, v249
	v_mov_b32_e32 v136, v250
	v_mov_b32_e32 v137, v251

.LBB0_843:
	v_mul_f32_e32 v134, v82, v215
	v_mul_f32_e32 v130, v134, v130
	v_mul_f32_e32 v134, v83, v215
	v_mul_f32_e32 v131, v134, v131
	v_mul_f32_e32 v134, v84, v215
	v_mul_f32_e32 v132, v134, v132
	v_mul_f32_e32 v134, v85, v215
	v_mul_f32_e32 v133, v134, v133
	ds_write_b128 v193, v[130:133] offset:33472
	v_mov_b32_e32 v133, 1.0
	s_and_b64 vcc, exec, s[6:7]
	v_mov_b32_e32 v137, 1.0
	v_mov_b32_e32 v136, 1.0
	v_mov_b32_e32 v135, 1.0
	v_mov_b32_e32 v134, 1.0
	s_cbranch_vccnz .LBB0_845
	v_mov_b32_e32 v134, v240
	v_mov_b32_e32 v135, v241
	v_mov_b32_e32 v136, v242
	v_mov_b32_e32 v137, v243
.LBB0_845:
	v_mul_f32_e32 v130, v78, v214
	v_mul_f32_e32 v134, v130, v134
	v_mul_f32_e32 v130, v79, v214
	v_mul_f32_e32 v135, v130, v135
	v_mul_f32_e32 v130, v80, v214
	v_mul_f32_e32 v136, v130, v136
	v_mul_f32_e32 v130, v81, v214
	v_mul_f32_e32 v137, v130, v137
	s_and_b64 vcc, exec, s[6:7]
	v_mov_b32_e32 v132, 1.0
	v_mov_b32_e32 v131, 1.0
	v_mov_b32_e32 v130, 1.0
	ds_write_b128 v193, v[134:137] offset:49920
	s_cbranch_vccnz .LBB0_847
	v_mov_b32_e32 v130, v244
	v_mov_b32_e32 v131, v245
	v_mov_b32_e32 v132, v246
	v_mov_b32_e32 v133, v247
.LBB0_847:
	v_mul_f32_e32 v134, v74, v214
	v_mul_f32_e32 v130, v134, v130
	v_mul_f32_e32 v134, v75, v214
	v_mul_f32_e32 v131, v134, v131
	v_mul_f32_e32 v134, v76, v214
	v_mul_f32_e32 v132, v134, v132
	v_mul_f32_e32 v134, v77, v214
	v_mul_f32_e32 v133, v134, v133
	ds_write_b128 v193, v[130:133] offset:49984
	v_mov_b32_e32 v133, 1.0
	s_and_b64 vcc, exec, s[6:7]
	v_mov_b32_e32 v137, 1.0
	v_mov_b32_e32 v136, 1.0
	v_mov_b32_e32 v135, 1.0
	v_mov_b32_e32 v134, 1.0
	s_cbranch_vccnz .LBB0_849
	v_mov_b32_e32 v134, v248
	v_mov_b32_e32 v135, v249
	v_mov_b32_e32 v136, v250
	v_mov_b32_e32 v137, v251

.LBB0_851:
	v_mul_f32_e32 v134, v66, v214
	v_mul_f32_e32 v130, v134, v130
	v_mul_f32_e32 v134, v67, v214
	v_mul_f32_e32 v131, v134, v131
	v_mul_f32_e32 v134, v68, v214
	v_mul_f32_e32 v132, v134, v132
	v_mul_f32_e32 v134, v69, v214
	v_mul_f32_e32 v133, v134, v133
	ds_write_b128 v193, v[130:133] offset:50112
	v_mov_b32_e32 v133, 1.0
	s_and_b64 vcc, exec, s[6:7]
	v_mov_b32_e32 v137, 1.0
	v_mov_b32_e32 v136, 1.0
	v_mov_b32_e32 v135, 1.0
	v_mov_b32_e32 v134, 1.0
	s_cbranch_vccnz .LBB0_853
	v_mov_b32_e32 v134, v240
	v_mov_b32_e32 v135, v241
	v_mov_b32_e32 v136, v242
	v_mov_b32_e32 v137, v243
.LBB0_853:
	v_mul_f32_e32 v130, v62, v213
	v_mul_f32_e32 v134, v130, v134
	v_mul_f32_e32 v130, v63, v213
	v_mul_f32_e32 v135, v130, v135
	v_mul_f32_e32 v130, v64, v213
	v_mul_f32_e32 v136, v130, v136
	v_mul_f32_e32 v130, v65, v213
	v_mul_f32_e32 v137, v130, v137
	v_add_u32_e32 v130, v197, v192
	ds_write_b128 v130, v[134:137]
	s_and_b64 vcc, exec, s[6:7]
	v_mov_b32_e32 v132, 1.0
	v_mov_b32_e32 v131, 1.0
	v_mov_b32_e32 v130, 1.0
	s_cbranch_vccnz .LBB0_855
	v_mov_b32_e32 v130, v244
	v_mov_b32_e32 v131, v245
	v_mov_b32_e32 v132, v246
	v_mov_b32_e32 v133, v247
.LBB0_855:
	v_mul_f32_e32 v134, v58, v213
	v_mul_f32_e32 v130, v134, v130
	v_mul_f32_e32 v134, v59, v213
	v_mul_f32_e32 v131, v134, v131
	v_mul_f32_e32 v134, v60, v213
	v_mul_f32_e32 v132, v134, v132
	v_mul_f32_e32 v134, v61, v213
	v_mul_f32_e32 v133, v134, v133
	v_add_u32_e32 v134, v197, v194
	ds_write_b128 v134, v[130:133]
	v_mov_b32_e32 v133, 1.0
	s_and_b64 vcc, exec, s[6:7]
	v_mov_b32_e32 v137, 1.0
	v_mov_b32_e32 v136, 1.0
	v_mov_b32_e32 v135, 1.0
	v_mov_b32_e32 v134, 1.0
	s_cbranch_vccnz .LBB0_857
	v_mov_b32_e32 v134, v248
	v_mov_b32_e32 v135, v249
	v_mov_b32_e32 v136, v250
	v_mov_b32_e32 v137, v251

.LBB0_859:
	v_mul_f32_e32 v134, v50, v213
	v_mul_f32_e32 v130, v134, v130
	v_mul_f32_e32 v134, v51, v213
	v_mul_f32_e32 v131, v134, v131
	v_mul_f32_e32 v134, v52, v213
	v_mul_f32_e32 v132, v134, v132
	v_mul_f32_e32 v134, v53, v213
	v_mul_f32_e32 v133, v134, v133
	v_add_u32_e32 v134, v197, v196
	ds_write_b128 v134, v[130:133]
	v_mov_b32_e32 v133, 1.0
	s_and_b64 vcc, exec, s[6:7]
	v_mov_b32_e32 v137, 1.0
	v_mov_b32_e32 v136, 1.0
	v_mov_b32_e32 v135, 1.0
	v_mov_b32_e32 v134, 1.0
	s_cbranch_vccnz .LBB0_861
	v_mov_b32_e32 v134, v240
	v_mov_b32_e32 v135, v241
	v_mov_b32_e32 v136, v242
	v_mov_b32_e32 v137, v243
.LBB0_861:
	v_mul_f32_e32 v130, v46, v212
	v_mul_f32_e32 v134, v130, v134
	v_mul_f32_e32 v130, v47, v212
	v_mul_f32_e32 v135, v130, v135
	v_mul_f32_e32 v130, v48, v212
	v_mul_f32_e32 v136, v130, v136
	v_mul_f32_e32 v130, v49, v212
	v_mul_f32_e32 v137, v130, v137
	v_add_u32_e32 v130, v198, v192
	ds_write_b128 v130, v[134:137]
	s_and_b64 vcc, exec, s[6:7]
	v_mov_b32_e32 v132, 1.0
	v_mov_b32_e32 v131, 1.0
	v_mov_b32_e32 v130, 1.0
	s_cbranch_vccnz .LBB0_863
	v_mov_b32_e32 v130, v244
	v_mov_b32_e32 v131, v245
	v_mov_b32_e32 v132, v246
	v_mov_b32_e32 v133, v247
.LBB0_863:
	v_mul_f32_e32 v134, v42, v212
	v_mul_f32_e32 v130, v134, v130
	v_mul_f32_e32 v134, v43, v212
	v_mul_f32_e32 v131, v134, v131
	v_mul_f32_e32 v134, v44, v212
	v_mul_f32_e32 v132, v134, v132
	v_mul_f32_e32 v134, v45, v212
	v_mul_f32_e32 v133, v134, v133
	v_add_u32_e32 v134, v198, v194
	ds_write_b128 v134, v[130:133]
	v_mov_b32_e32 v133, 1.0
	s_and_b64 vcc, exec, s[6:7]
	v_mov_b32_e32 v137, 1.0
	v_mov_b32_e32 v136, 1.0
	v_mov_b32_e32 v135, 1.0
	v_mov_b32_e32 v134, 1.0
	s_cbranch_vccnz .LBB0_865
	v_mov_b32_e32 v134, v248
	v_mov_b32_e32 v135, v249
	v_mov_b32_e32 v136, v250
	v_mov_b32_e32 v137, v251

.LBB0_867:
	v_mul_f32_e32 v134, v34, v212
	v_mul_f32_e32 v130, v134, v130
	v_mul_f32_e32 v134, v35, v212
	v_mul_f32_e32 v131, v134, v131
	v_mul_f32_e32 v134, v36, v212
	v_mul_f32_e32 v132, v134, v132
	v_mul_f32_e32 v134, v37, v212
	v_mul_f32_e32 v133, v134, v133
	v_add_u32_e32 v134, v198, v196
	ds_write_b128 v134, v[130:133]
	v_mov_b32_e32 v133, 1.0
	s_and_b64 vcc, exec, s[6:7]
	v_mov_b32_e32 v137, 1.0
	v_mov_b32_e32 v136, 1.0
	v_mov_b32_e32 v135, 1.0
	v_mov_b32_e32 v134, 1.0
	s_cbranch_vccnz .LBB0_869
	v_mov_b32_e32 v134, v240
	v_mov_b32_e32 v135, v241
	v_mov_b32_e32 v136, v242
	v_mov_b32_e32 v137, v243
.LBB0_869:
	v_mul_f32_e32 v130, v30, v211
	v_mul_f32_e32 v134, v130, v134
	v_mul_f32_e32 v130, v31, v211
	v_mul_f32_e32 v135, v130, v135
	v_mul_f32_e32 v130, v32, v211
	v_mul_f32_e32 v136, v130, v136
	v_mul_f32_e32 v130, v33, v211
	v_mul_f32_e32 v137, v130, v137
	v_add_u32_e32 v130, v199, v192
	ds_write_b128 v130, v[134:137]
	s_and_b64 vcc, exec, s[6:7]
	v_mov_b32_e32 v132, 1.0
	v_mov_b32_e32 v131, 1.0
	v_mov_b32_e32 v130, 1.0
	s_cbranch_vccnz .LBB0_871
	v_mov_b32_e32 v130, v244
	v_mov_b32_e32 v131, v245
	v_mov_b32_e32 v132, v246
	v_mov_b32_e32 v133, v247
.LBB0_871:
	v_mul_f32_e32 v134, v26, v211
	v_mul_f32_e32 v130, v134, v130
	v_mul_f32_e32 v134, v27, v211
	v_mul_f32_e32 v131, v134, v131
	v_mul_f32_e32 v134, v28, v211
	v_mul_f32_e32 v132, v134, v132
	v_mul_f32_e32 v134, v29, v211
	v_mul_f32_e32 v133, v134, v133
	v_add_u32_e32 v134, v199, v194
	ds_write_b128 v134, v[130:133]
	v_mov_b32_e32 v133, 1.0
	s_and_b64 vcc, exec, s[6:7]
	v_mov_b32_e32 v137, 1.0
	v_mov_b32_e32 v136, 1.0
	v_mov_b32_e32 v135, 1.0
	v_mov_b32_e32 v134, 1.0
	s_cbranch_vccnz .LBB0_873
	v_mov_b32_e32 v134, v248
	v_mov_b32_e32 v135, v249
	v_mov_b32_e32 v136, v250
	v_mov_b32_e32 v137, v251

.LBB0_875:
	v_mul_f32_e32 v134, v18, v211
	v_mul_f32_e32 v130, v134, v130
	v_mul_f32_e32 v134, v19, v211
	v_mul_f32_e32 v131, v134, v131
	v_mul_f32_e32 v134, v20, v211
	v_mul_f32_e32 v132, v134, v132
	v_mul_f32_e32 v134, v21, v211
	v_mul_f32_e32 v133, v134, v133
	v_add_u32_e32 v134, v199, v196
	ds_write_b128 v134, v[130:133]
	v_mov_b32_e32 v133, 1.0
	s_and_b64 vcc, exec, s[6:7]
	v_mov_b32_e32 v137, 1.0
	v_mov_b32_e32 v136, 1.0
	v_mov_b32_e32 v135, 1.0
	v_mov_b32_e32 v134, 1.0
	s_cbranch_vccnz .LBB0_877
	v_mov_b32_e32 v134, v240
	v_mov_b32_e32 v135, v241
	v_mov_b32_e32 v136, v242
	v_mov_b32_e32 v137, v243
.LBB0_877:
	v_mul_f32_e32 v130, v14, v210
	v_mul_f32_e32 v134, v130, v134
	v_mul_f32_e32 v130, v15, v210
	v_mul_f32_e32 v135, v130, v135
	v_mul_f32_e32 v130, v16, v210
	v_mul_f32_e32 v136, v130, v136
	v_mul_f32_e32 v130, v17, v210
	v_mul_f32_e32 v137, v130, v137
	v_add_u32_e32 v130, v200, v192
	ds_write_b128 v130, v[134:137]
	s_and_b64 vcc, exec, s[6:7]
	v_mov_b32_e32 v132, 1.0
	v_mov_b32_e32 v131, 1.0
	v_mov_b32_e32 v130, 1.0
	s_cbranch_vccnz .LBB0_879
	v_mov_b32_e32 v130, v244
	v_mov_b32_e32 v131, v245
	v_mov_b32_e32 v132, v246
	v_mov_b32_e32 v133, v247
.LBB0_879:
	v_mul_f32_e32 v134, v10, v210
	v_mul_f32_e32 v130, v134, v130
	v_mul_f32_e32 v134, v11, v210
	v_mul_f32_e32 v131, v134, v131
	v_mul_f32_e32 v134, v12, v210
	v_mul_f32_e32 v132, v134, v132
	v_mul_f32_e32 v134, v13, v210
	v_mul_f32_e32 v133, v134, v133
	v_add_u32_e32 v134, v200, v194
	ds_write_b128 v134, v[130:133]
	v_mov_b32_e32 v133, 1.0
	s_and_b64 vcc, exec, s[6:7]
	v_mov_b32_e32 v137, 1.0
	v_mov_b32_e32 v136, 1.0
	v_mov_b32_e32 v135, 1.0
	v_mov_b32_e32 v134, 1.0
	s_cbranch_vccnz .LBB0_881
	v_mov_b32_e32 v134, v248
	v_mov_b32_e32 v135, v249
	v_mov_b32_e32 v136, v250
	v_mov_b32_e32 v137, v251

.LBB0_885:
	ds_read_b128 v[140:143], v135
	ds_read_b128 v[218:221], v134
	ds_read_b128 v[222:225], v134 offset:16640
	ds_read_b128 v[226:229], v138
	v_lshl_add_u64 v[144:145], v[136:137], 0, s[44:45]
	v_lshl_add_u64 v[230:231], v[132:133], 0, s[44:45]
	v_lshl_add_u64 v[232:233], v[130:131], 0, s[44:45]
	s_add_u32 s44, s44, 0x40000
	s_addc_u32 s45, s45, 0
	v_add_u32_e32 v138, 0x8200, v138
	v_add_u32_e32 v135, 0x8200, v135
	v_add_u32_e32 v134, 0x8200, v134
	v_add_co_u32_e32 v234, vcc, 0x20000, v144
	s_cmp_eq_u32 s44, 0x100000
	s_nop 0
	v_addc_co_u32_e32 v235, vcc, 0, v145, vcc
	s_waitcnt lgkmcnt(2)
	global_store_dwordx4 v[144:145], v[218:221], off nt
	global_store_dwordx4 v[230:231], v[140:143], off nt
	s_waitcnt lgkmcnt(1)
	global_store_dwordx4 v[234:235], v[222:225], off nt
	s_waitcnt lgkmcnt(0)
	global_store_dwordx4 v[232:233], v[226:229], off nt
	s_cbranch_scc0 .LBB0_885
	s_barrier
	s_and_saveexec_b64 s[44:45], s[4:5]
	s_cbranch_execz .LBB0_952
	v_mov_b32_e32 v131, 1.0
	s_and_b64 vcc, exec, s[6:7]
	v_mov_b32_e32 v135, 1.0
	v_mov_b32_e32 v134, 1.0
	v_mov_b32_e32 v133, 1.0
	v_mov_b32_e32 v132, 1.0
	s_cbranch_vccnz .LBB0_889
	v_mov_b32_e32 v132, v240
	v_mov_b32_e32 v133, v241
	v_mov_b32_e32 v134, v242
	v_mov_b32_e32 v135, v243
.LBB0_889:
	v_mul_f32_e32 v126, v126, v217
	v_mul_f32_e32 v127, v127, v217
	v_mul_f32_e32 v128, v128, v217
	v_mul_f32_e32 v129, v129, v217
	v_mul_f32_e32 v126, v126, v132
	v_mul_f32_e32 v127, v127, v133
	v_mul_f32_e32 v128, v128, v134
	v_mul_f32_e32 v129, v129, v135
	ds_write_b128 v193, v[126:129]
	s_and_b64 vcc, exec, s[6:7]
	v_mov_b32_e32 v130, 1.0
	v_mov_b32_e32 v129, 1.0
	v_mov_b32_e32 v128, 1.0
	s_cbranch_vccnz .LBB0_891
	v_mov_b32_e32 v128, v244
	v_mov_b32_e32 v129, v245
	v_mov_b32_e32 v130, v246
	v_mov_b32_e32 v131, v247
.LBB0_891:
	v_mul_f32_e32 v122, v122, v217
	v_mul_f32_e32 v123, v123, v217
	v_mul_f32_e32 v124, v124, v217
	v_mul_f32_e32 v125, v125, v217
	v_mul_f32_e32 v122, v122, v128
	v_mul_f32_e32 v123, v123, v129
	v_mul_f32_e32 v124, v124, v130
	v_mul_f32_e32 v125, v125, v131
	ds_write_b128 v193, v[122:125] offset:64
	v_mov_b32_e32 v123, 1.0
	s_and_b64 vcc, exec, s[6:7]
	v_mov_b32_e32 v127, 1.0
	v_mov_b32_e32 v126, 1.0
	v_mov_b32_e32 v125, 1.0
	v_mov_b32_e32 v124, 1.0
	s_cbranch_vccnz .LBB0_893
	v_mov_b32_e32 v124, v248
	v_mov_b32_e32 v125, v249
	v_mov_b32_e32 v126, v250
	v_mov_b32_e32 v127, v251

.LBB0_895:
	v_mul_f32_e32 v114, v114, v217
	v_mul_f32_e32 v115, v115, v217
	v_mul_f32_e32 v116, v116, v217
	v_mul_f32_e32 v117, v117, v217
	v_mul_f32_e32 v114, v114, v120
	v_mul_f32_e32 v115, v115, v121
	v_mul_f32_e32 v116, v116, v122
	v_mul_f32_e32 v117, v117, v123
	ds_write_b128 v193, v[114:117] offset:192
	v_mov_b32_e32 v115, 1.0
	s_and_b64 vcc, exec, s[6:7]
	v_mov_b32_e32 v119, 1.0
	v_mov_b32_e32 v118, 1.0
	v_mov_b32_e32 v117, 1.0
	v_mov_b32_e32 v116, 1.0
	s_cbranch_vccnz .LBB0_897
	v_mov_b32_e32 v116, v240
	v_mov_b32_e32 v117, v241
	v_mov_b32_e32 v118, v242
	v_mov_b32_e32 v119, v243
.LBB0_897:
	v_mul_f32_e32 v110, v110, v216
	v_mul_f32_e32 v111, v111, v216
	v_mul_f32_e32 v112, v112, v216
	v_mul_f32_e32 v113, v113, v216
	v_mul_f32_e32 v110, v110, v116
	v_mul_f32_e32 v111, v111, v117
	v_mul_f32_e32 v112, v112, v118
	v_mul_f32_e32 v113, v113, v119
	ds_write_b128 v193, v[110:113] offset:16640
	s_and_b64 vcc, exec, s[6:7]
	v_mov_b32_e32 v114, 1.0
	v_mov_b32_e32 v113, 1.0
	v_mov_b32_e32 v112, 1.0
	s_cbranch_vccnz .LBB0_899
	v_mov_b32_e32 v112, v244
	v_mov_b32_e32 v113, v245
	v_mov_b32_e32 v114, v246
	v_mov_b32_e32 v115, v247
.LBB0_899:
	v_mul_f32_e32 v106, v106, v216
	v_mul_f32_e32 v107, v107, v216
	v_mul_f32_e32 v108, v108, v216
	v_mul_f32_e32 v109, v109, v216
	v_mul_f32_e32 v106, v106, v112
	v_mul_f32_e32 v107, v107, v113
	v_mul_f32_e32 v108, v108, v114
	v_mul_f32_e32 v109, v109, v115
	ds_write_b128 v193, v[106:109] offset:16704
	v_mov_b32_e32 v107, 1.0
	s_and_b64 vcc, exec, s[6:7]
	v_mov_b32_e32 v111, 1.0
	v_mov_b32_e32 v110, 1.0
	v_mov_b32_e32 v109, 1.0
	v_mov_b32_e32 v108, 1.0
	s_cbranch_vccnz .LBB0_901
	v_mov_b32_e32 v108, v248
	v_mov_b32_e32 v109, v249
	v_mov_b32_e32 v110, v250
	v_mov_b32_e32 v111, v251

.LBB0_903:
	v_mul_f32_e32 v98, v98, v216
	v_mul_f32_e32 v99, v99, v216
	v_mul_f32_e32 v100, v100, v216
	v_mul_f32_e32 v101, v101, v216
	v_mul_f32_e32 v98, v98, v104
	v_mul_f32_e32 v99, v99, v105
	v_mul_f32_e32 v100, v100, v106
	v_mul_f32_e32 v101, v101, v107
	ds_write_b128 v193, v[98:101] offset:16832
	v_mov_b32_e32 v99, 1.0
	s_and_b64 vcc, exec, s[6:7]
	v_mov_b32_e32 v103, 1.0
	v_mov_b32_e32 v102, 1.0
	v_mov_b32_e32 v101, 1.0
	v_mov_b32_e32 v100, 1.0
	s_cbranch_vccnz .LBB0_905
	v_mov_b32_e32 v100, v240
	v_mov_b32_e32 v101, v241
	v_mov_b32_e32 v102, v242
	v_mov_b32_e32 v103, v243
.LBB0_905:
	v_mul_f32_e32 v94, v94, v215
	v_mul_f32_e32 v95, v95, v215
	v_mul_f32_e32 v96, v96, v215
	v_mul_f32_e32 v97, v97, v215
	v_mul_f32_e32 v94, v94, v100
	v_mul_f32_e32 v95, v95, v101
	v_mul_f32_e32 v96, v96, v102
	v_mul_f32_e32 v97, v97, v103
	ds_write_b128 v193, v[94:97] offset:33280
	s_and_b64 vcc, exec, s[6:7]
	v_mov_b32_e32 v98, 1.0
	v_mov_b32_e32 v97, 1.0
	v_mov_b32_e32 v96, 1.0
	s_cbranch_vccnz .LBB0_907
	v_mov_b32_e32 v96, v244
	v_mov_b32_e32 v97, v245
	v_mov_b32_e32 v98, v246
	v_mov_b32_e32 v99, v247
.LBB0_907:
	v_mul_f32_e32 v90, v90, v215
	v_mul_f32_e32 v91, v91, v215
	v_mul_f32_e32 v92, v92, v215
	v_mul_f32_e32 v93, v93, v215
	v_mul_f32_e32 v90, v90, v96
	v_mul_f32_e32 v91, v91, v97
	v_mul_f32_e32 v92, v92, v98
	v_mul_f32_e32 v93, v93, v99
	ds_write_b128 v193, v[90:93] offset:33344
	v_mov_b32_e32 v91, 1.0
	s_and_b64 vcc, exec, s[6:7]
	v_mov_b32_e32 v95, 1.0
	v_mov_b32_e32 v94, 1.0
	v_mov_b32_e32 v93, 1.0
	v_mov_b32_e32 v92, 1.0
	s_cbranch_vccnz .LBB0_909
	v_mov_b32_e32 v92, v248
	v_mov_b32_e32 v93, v249
	v_mov_b32_e32 v94, v250
	v_mov_b32_e32 v95, v251

.LBB0_911:
	v_mul_f32_e32 v82, v82, v215
	v_mul_f32_e32 v83, v83, v215
	v_mul_f32_e32 v84, v84, v215
	v_mul_f32_e32 v85, v85, v215
	v_mul_f32_e32 v82, v82, v88
	v_mul_f32_e32 v83, v83, v89
	v_mul_f32_e32 v84, v84, v90
	v_mul_f32_e32 v85, v85, v91
	ds_write_b128 v193, v[82:85] offset:33472
	v_mov_b32_e32 v83, 1.0
	s_and_b64 vcc, exec, s[6:7]
	v_mov_b32_e32 v87, 1.0
	v_mov_b32_e32 v86, 1.0
	v_mov_b32_e32 v85, 1.0
	v_mov_b32_e32 v84, 1.0
	s_cbranch_vccnz .LBB0_913
	v_mov_b32_e32 v84, v240
	v_mov_b32_e32 v85, v241
	v_mov_b32_e32 v86, v242
	v_mov_b32_e32 v87, v243
.LBB0_913:
	v_mul_f32_e32 v78, v78, v214
	v_mul_f32_e32 v79, v79, v214
	v_mul_f32_e32 v80, v80, v214
	v_mul_f32_e32 v81, v81, v214
	v_mul_f32_e32 v78, v78, v84
	v_mul_f32_e32 v79, v79, v85
	v_mul_f32_e32 v80, v80, v86
	v_mul_f32_e32 v81, v81, v87
	ds_write_b128 v193, v[78:81] offset:49920
	s_and_b64 vcc, exec, s[6:7]
	v_mov_b32_e32 v82, 1.0
	v_mov_b32_e32 v81, 1.0
	v_mov_b32_e32 v80, 1.0
	s_cbranch_vccnz .LBB0_915
	v_mov_b32_e32 v80, v244
	v_mov_b32_e32 v81, v245
	v_mov_b32_e32 v82, v246
	v_mov_b32_e32 v83, v247
.LBB0_915:
	v_mul_f32_e32 v74, v74, v214
	v_mul_f32_e32 v75, v75, v214
	v_mul_f32_e32 v76, v76, v214
	v_mul_f32_e32 v77, v77, v214
	v_mul_f32_e32 v74, v74, v80
	v_mul_f32_e32 v75, v75, v81
	v_mul_f32_e32 v76, v76, v82
	v_mul_f32_e32 v77, v77, v83
	ds_write_b128 v193, v[74:77] offset:49984
	v_mov_b32_e32 v75, 1.0
	s_and_b64 vcc, exec, s[6:7]
	v_mov_b32_e32 v79, 1.0
	v_mov_b32_e32 v78, 1.0
	v_mov_b32_e32 v77, 1.0
	v_mov_b32_e32 v76, 1.0
	s_cbranch_vccnz .LBB0_917
	v_mov_b32_e32 v76, v248
	v_mov_b32_e32 v77, v249
	v_mov_b32_e32 v78, v250
	v_mov_b32_e32 v79, v251

.LBB0_919:
	v_mul_f32_e32 v66, v66, v214
	v_mul_f32_e32 v67, v67, v214
	v_mul_f32_e32 v68, v68, v214
	v_mul_f32_e32 v69, v69, v214
	v_mul_f32_e32 v66, v66, v72
	v_mul_f32_e32 v67, v67, v73
	v_mul_f32_e32 v68, v68, v74
	v_mul_f32_e32 v69, v69, v75
	ds_write_b128 v193, v[66:69] offset:50112
	v_mov_b32_e32 v67, 1.0
	s_and_b64 vcc, exec, s[6:7]
	v_mov_b32_e32 v71, 1.0
	v_mov_b32_e32 v70, 1.0
	v_mov_b32_e32 v69, 1.0
	v_mov_b32_e32 v68, 1.0
	s_cbranch_vccnz .LBB0_921
	v_mov_b32_e32 v68, v240
	v_mov_b32_e32 v69, v241
	v_mov_b32_e32 v70, v242
	v_mov_b32_e32 v71, v243
.LBB0_921:
	v_mul_f32_e32 v62, v62, v213
	v_mul_f32_e32 v63, v63, v213
	v_mul_f32_e32 v64, v64, v213
	v_mul_f32_e32 v65, v65, v213
	v_mul_f32_e32 v62, v62, v68
	v_mul_f32_e32 v63, v63, v69
	v_mul_f32_e32 v64, v64, v70
	v_mul_f32_e32 v65, v65, v71
	v_add_u32_e32 v66, v197, v192
	ds_write_b128 v66, v[62:65]
	s_and_b64 vcc, exec, s[6:7]
	v_mov_b32_e32 v66, 1.0
	v_mov_b32_e32 v65, 1.0
	v_mov_b32_e32 v64, 1.0
	s_cbranch_vccnz .LBB0_923
	v_mov_b32_e32 v64, v244
	v_mov_b32_e32 v65, v245
	v_mov_b32_e32 v66, v246
	v_mov_b32_e32 v67, v247
.LBB0_923:
	v_mul_f32_e32 v58, v58, v213
	v_mul_f32_e32 v59, v59, v213
	v_mul_f32_e32 v60, v60, v213
	v_mul_f32_e32 v61, v61, v213
	v_mul_f32_e32 v58, v58, v64
	v_mul_f32_e32 v59, v59, v65
	v_mul_f32_e32 v60, v60, v66
	v_mul_f32_e32 v61, v61, v67
	v_add_u32_e32 v62, v197, v194
	ds_write_b128 v62, v[58:61]
	v_mov_b32_e32 v59, 1.0
	s_and_b64 vcc, exec, s[6:7]
	v_mov_b32_e32 v63, 1.0
	v_mov_b32_e32 v62, 1.0
	v_mov_b32_e32 v61, 1.0
	v_mov_b32_e32 v60, 1.0
	s_cbranch_vccnz .LBB0_925
	v_mov_b32_e32 v60, v248
	v_mov_b32_e32 v61, v249
	v_mov_b32_e32 v62, v250
	v_mov_b32_e32 v63, v251

.LBB0_927:
	v_mul_f32_e32 v50, v50, v213
	v_mul_f32_e32 v51, v51, v213
	v_mul_f32_e32 v52, v52, v213
	v_mul_f32_e32 v53, v53, v213
	v_mul_f32_e32 v50, v50, v56
	v_mul_f32_e32 v51, v51, v57
	v_mul_f32_e32 v52, v52, v58
	v_mul_f32_e32 v53, v53, v59
	v_add_u32_e32 v54, v197, v196
	ds_write_b128 v54, v[50:53]
	v_mov_b32_e32 v51, 1.0
	s_and_b64 vcc, exec, s[6:7]
	v_mov_b32_e32 v55, 1.0
	v_mov_b32_e32 v54, 1.0
	v_mov_b32_e32 v53, 1.0
	v_mov_b32_e32 v52, 1.0
	s_cbranch_vccnz .LBB0_929
	v_mov_b32_e32 v52, v240
	v_mov_b32_e32 v53, v241
	v_mov_b32_e32 v54, v242
	v_mov_b32_e32 v55, v243
.LBB0_929:
	v_mul_f32_e32 v46, v46, v212
	v_mul_f32_e32 v47, v47, v212
	v_mul_f32_e32 v48, v48, v212
	v_mul_f32_e32 v49, v49, v212
	v_mul_f32_e32 v46, v46, v52
	v_mul_f32_e32 v47, v47, v53
	v_mul_f32_e32 v48, v48, v54
	v_mul_f32_e32 v49, v49, v55
	v_add_u32_e32 v50, v198, v192
	ds_write_b128 v50, v[46:49]
	s_and_b64 vcc, exec, s[6:7]
	v_mov_b32_e32 v50, 1.0
	v_mov_b32_e32 v49, 1.0
	v_mov_b32_e32 v48, 1.0
	s_cbranch_vccnz .LBB0_931
	v_mov_b32_e32 v48, v244
	v_mov_b32_e32 v49, v245
	v_mov_b32_e32 v50, v246
	v_mov_b32_e32 v51, v247
.LBB0_931:
	v_mul_f32_e32 v42, v42, v212
	v_mul_f32_e32 v43, v43, v212
	v_mul_f32_e32 v44, v44, v212
	v_mul_f32_e32 v45, v45, v212
	v_mul_f32_e32 v42, v42, v48
	v_mul_f32_e32 v43, v43, v49
	v_mul_f32_e32 v44, v44, v50
	v_mul_f32_e32 v45, v45, v51
	v_add_u32_e32 v46, v198, v194
	ds_write_b128 v46, v[42:45]
	v_mov_b32_e32 v43, 1.0
	s_and_b64 vcc, exec, s[6:7]
	v_mov_b32_e32 v47, 1.0
	v_mov_b32_e32 v46, 1.0
	v_mov_b32_e32 v45, 1.0
	v_mov_b32_e32 v44, 1.0
	s_cbranch_vccnz .LBB0_933
	v_mov_b32_e32 v44, v248
	v_mov_b32_e32 v45, v249
	v_mov_b32_e32 v46, v250
	v_mov_b32_e32 v47, v251

.LBB0_935:
	v_mul_f32_e32 v34, v34, v212
	v_mul_f32_e32 v35, v35, v212
	v_mul_f32_e32 v36, v36, v212
	v_mul_f32_e32 v37, v37, v212
	v_mul_f32_e32 v34, v34, v40
	v_mul_f32_e32 v35, v35, v41
	v_mul_f32_e32 v36, v36, v42
	v_mul_f32_e32 v37, v37, v43
	v_add_u32_e32 v38, v198, v196
	ds_write_b128 v38, v[34:37]
	v_mov_b32_e32 v35, 1.0
	s_and_b64 vcc, exec, s[6:7]
	v_mov_b32_e32 v39, 1.0
	v_mov_b32_e32 v38, 1.0
	v_mov_b32_e32 v37, 1.0
	v_mov_b32_e32 v36, 1.0
	s_cbranch_vccnz .LBB0_937
	v_mov_b32_e32 v36, v240
	v_mov_b32_e32 v37, v241
	v_mov_b32_e32 v38, v242
	v_mov_b32_e32 v39, v243
.LBB0_937:
	v_mul_f32_e32 v30, v30, v211
	v_mul_f32_e32 v31, v31, v211
	v_mul_f32_e32 v32, v32, v211
	v_mul_f32_e32 v33, v33, v211
	v_mul_f32_e32 v30, v30, v36
	v_mul_f32_e32 v31, v31, v37
	v_mul_f32_e32 v32, v32, v38
	v_mul_f32_e32 v33, v33, v39
	v_add_u32_e32 v34, v199, v192
	ds_write_b128 v34, v[30:33]
	s_and_b64 vcc, exec, s[6:7]
	v_mov_b32_e32 v34, 1.0
	v_mov_b32_e32 v33, 1.0
	v_mov_b32_e32 v32, 1.0
	s_cbranch_vccnz .LBB0_939
	v_mov_b32_e32 v32, v244
	v_mov_b32_e32 v33, v245
	v_mov_b32_e32 v34, v246
	v_mov_b32_e32 v35, v247
.LBB0_939:
	v_mul_f32_e32 v26, v26, v211
	v_mul_f32_e32 v27, v27, v211
	v_mul_f32_e32 v28, v28, v211
	v_mul_f32_e32 v29, v29, v211
	v_mul_f32_e32 v26, v26, v32
	v_mul_f32_e32 v27, v27, v33
	v_mul_f32_e32 v28, v28, v34
	v_mul_f32_e32 v29, v29, v35
	v_add_u32_e32 v30, v199, v194
	ds_write_b128 v30, v[26:29]
	v_mov_b32_e32 v27, 1.0
	s_and_b64 vcc, exec, s[6:7]
	v_mov_b32_e32 v31, 1.0
	v_mov_b32_e32 v30, 1.0
	v_mov_b32_e32 v29, 1.0
	v_mov_b32_e32 v28, 1.0
	s_cbranch_vccnz .LBB0_941
	v_mov_b32_e32 v28, v248
	v_mov_b32_e32 v29, v249
	v_mov_b32_e32 v30, v250
	v_mov_b32_e32 v31, v251

.LBB0_943:
	v_mul_f32_e32 v18, v18, v211
	v_mul_f32_e32 v19, v19, v211
	v_mul_f32_e32 v20, v20, v211
	v_mul_f32_e32 v21, v21, v211
	v_mul_f32_e32 v18, v18, v24
	v_mul_f32_e32 v19, v19, v25
	v_mul_f32_e32 v20, v20, v26
	v_mul_f32_e32 v21, v21, v27
	v_add_u32_e32 v22, v199, v196
	ds_write_b128 v22, v[18:21]
	v_mov_b32_e32 v19, 1.0
	s_and_b64 vcc, exec, s[6:7]
	v_mov_b32_e32 v23, 1.0
	v_mov_b32_e32 v22, 1.0
	v_mov_b32_e32 v21, 1.0
	v_mov_b32_e32 v20, 1.0
	s_cbranch_vccnz .LBB0_945
	v_mov_b32_e32 v20, v240
	v_mov_b32_e32 v21, v241
	v_mov_b32_e32 v22, v242
	v_mov_b32_e32 v23, v243
.LBB0_945:
	v_mul_f32_e32 v14, v14, v210
	v_mul_f32_e32 v15, v15, v210
	v_mul_f32_e32 v16, v16, v210
	v_mul_f32_e32 v17, v17, v210
	v_mul_f32_e32 v14, v14, v20
	v_mul_f32_e32 v15, v15, v21
	v_mul_f32_e32 v16, v16, v22
	v_mul_f32_e32 v17, v17, v23
	v_add_u32_e32 v18, v200, v192
	ds_write_b128 v18, v[14:17]
	s_and_b64 vcc, exec, s[6:7]
	v_mov_b32_e32 v18, 1.0
	v_mov_b32_e32 v17, 1.0
	v_mov_b32_e32 v16, 1.0
	s_cbranch_vccnz .LBB0_947
	v_mov_b32_e32 v16, v244
	v_mov_b32_e32 v17, v245
	v_mov_b32_e32 v18, v246
	v_mov_b32_e32 v19, v247
.LBB0_947:
	v_mul_f32_e32 v10, v10, v210
	v_mul_f32_e32 v11, v11, v210
	v_mul_f32_e32 v12, v12, v210
	v_mul_f32_e32 v13, v13, v210
	v_mul_f32_e32 v10, v10, v16
	v_mul_f32_e32 v11, v11, v17
	v_mul_f32_e32 v12, v12, v18
	v_mul_f32_e32 v13, v13, v19
	v_add_u32_e32 v14, v200, v194
	ds_write_b128 v14, v[10:13]
	v_mov_b32_e32 v11, 1.0
	s_and_b64 vcc, exec, s[6:7]
	v_mov_b32_e32 v15, 1.0
	v_mov_b32_e32 v14, 1.0
	v_mov_b32_e32 v13, 1.0
	v_mov_b32_e32 v12, 1.0
	s_cbranch_vccnz .LBB0_949
	v_mov_b32_e32 v12, v248
	v_mov_b32_e32 v13, v249
	v_mov_b32_e32 v14, v250
	v_mov_b32_e32 v15, v251
